# attention s-loop: the 4 gate-row (z) loads addressed by one SALU-advanced SGPR base + loop-invariant VGPR offsets; ~36 VALU address instructions (4 v_mad_u64_u32) removed per iteration
# speedup vs baseline: 1.0064x; 1.0051x over previous
.Lattn_stage_k23:
	global_load_dwordx4 v[12:15], v252, s[86:87] offset:3072
	global_load_dwordx4 v[230:233], v253, s[86:87] offset:3072
	s_mov_b32 s69, 0
	s_lshl_b32 s70, s68, 3
	s_add_i32 s76, s70, s3
	v_or_b32_e32 v2, s66, v124
	v_mov_b64_e32 v[0:1], s[50:51]
	s_lshl_b32 s84, s76, 6
	v_mad_u64_u32 v[0:1], s[70:71], v2, s95, v[0:1]
	s_ashr_i32 s85, s84, 31
	v_mad_i32_i24 v1, s67, v187, v1
	s_lshl_b64 s[70:71], s[84:85], 1
	s_ashr_i32 s77, s76, 31
	v_lshl_add_u64 v[0:1], v[0:1], 0, s[70:71]
	v_lshlrev_b32_e32 v126, 1, v141
	s_lshl_b64 s[76:77], s[76:77], 2
	v_lshl_add_u64 v[0:1], v[0:1], 0, v[126:127]
	s_add_u32 s76, s78, s76
	global_load_dwordx4 v[48:51], v[0:1], off nt
	global_load_dwordx4 v[108:111], v[0:1], off offset:32 nt
	global_load_dwordx4 v[104:107], v[0:1], off offset:64 nt
	global_load_dwordx4 v[120:123], v[0:1], off offset:96 nt
	s_addc_u32 s77, s79, s77
	global_load_dword v16, v127, s[76:77]
	v_lshl_add_u64 v[0:1], s[84:85], 2, v[138:139]
	global_load_dwordx4 v[80:83], v[0:1], off
	global_load_dwordx4 v[84:87], v[0:1], off offset:16
	s_waitcnt vmcnt(8)
	ds_write_b128 v186, v[4:7]
	ds_write_b128 v176, v[8:11]
	ds_write_b128 v177, v[12:15]
	ds_write_b16 v179, v234 offset:36864
	ds_write_b16_d16_hi v179, v234 offset:37392
	ds_write_b16 v179, v235 offset:37920
	ds_write_b16_d16_hi v179, v235 offset:38448
	ds_write_b16 v179, v236 offset:38976
	ds_write_b16_d16_hi v179, v236 offset:39504
	ds_write_b16 v179, v237 offset:40032
	ds_write_b16_d16_hi v179, v237 offset:40560
	ds_write_b16 v180, v238 offset:36864
	ds_write_b16_d16_hi v180, v238 offset:37392
	ds_write_b16 v180, v239 offset:37920
	ds_write_b16_d16_hi v180, v239 offset:38448
	ds_write_b16 v180, v240 offset:38976
	ds_write_b16_d16_hi v180, v240 offset:39504
	ds_write_b16 v180, v241 offset:40032
	ds_write_b16_d16_hi v180, v241 offset:40560
	ds_write_b16 v181, v242 offset:36864
	ds_write_b16_d16_hi v181, v242 offset:37392
	ds_write_b16 v181, v243 offset:37920
	ds_write_b16_d16_hi v181, v243 offset:38448
	ds_write_b16 v181, v244 offset:38976
	ds_write_b16_d16_hi v181, v244 offset:39504
	ds_write_b16 v181, v245 offset:40032
	ds_write_b16_d16_hi v181, v245 offset:40560
	ds_write_b16 v182, v246 offset:36864
	ds_write_b16_d16_hi v182, v246 offset:37392
	ds_write_b16 v182, v247 offset:37920
	ds_write_b16_d16_hi v182, v247 offset:38448
	ds_write_b16 v182, v248 offset:38976
	ds_write_b16_d16_hi v182, v248 offset:39504
	ds_write_b16 v182, v249 offset:40032
	ds_write_b16_d16_hi v182, v249 offset:40560
	s_waitcnt vmcnt(7)
	ds_write_b128 v178, v[230:233]
	s_waitcnt lgkmcnt(0)
	s_barrier
	s_mul_i32 s85, s72, 0x9000000
	s_cmp_eq_u32 s99, 0
	s_mul_hi_i32 s84, s72, 0x9000000
	v_lshl_add_u64 v[0:1], v[124:125], 0, s[74:75]
	s_cselect_b64 s[72:73], -1, 0
	s_add_u32 s74, s70, s85
	s_addc_u32 s75, s71, s84
	v_mov_b64_e32 v[2:3], s[74:75]
	v_mad_u64_u32 v[2:3], s[74:75], v0, s95, v[2:3]
	v_mad_i32_i24 v3, v1, s95, v3
	v_mov_b32_e32 v151, v173
	v_mov_b32_e32 v153, v172
	s_mov_b32 s76, 0
	s_mov_b32 s77, 0
	v_lshl_add_u64 v[162:163], v[142:143], 0, s[70:71]
	v_lshl_add_u64 v[164:165], v[148:149], 0, v[2:3]
	s_waitcnt vmcnt(6)
	v_mov_b64_e32 v[90:91], v[50:51]
	s_waitcnt vmcnt(5)
	v_mov_b64_e32 v[92:93], v[108:109]
	s_waitcnt vmcnt(4)
	v_mov_b64_e32 v[96:97], v[104:105]
	s_waitcnt vmcnt(3)
	v_mov_b64_e32 v[100:101], v[120:121]
	v_mov_b64_e32 v[88:89], v[48:49]
	v_mov_b64_e32 v[94:95], v[110:111]
	v_mov_b64_e32 v[98:99], v[106:107]
	v_mov_b64_e32 v[102:103], v[122:123]
	s_waitcnt vmcnt(2)
	v_mul_f32_e32 v155, 0x3fb8aa3b, v16
	v_mul_u32_u24_e32 v231, 0x2400, v145
	v_add_u32_e32 v231, v231, v160
	v_add_u32_e32 v232, 0x12000, v231
	v_add_u32_e32 v233, 0x24000, v231
	v_add_u32_e32 v234, 0x36000, v231
	s_branch .LBB0_315

.LBB0_317:
	s_add_u32 s100, s66, s84
	s_mul_i32 s100, s100, 0x2400
	s_add_u32 s100, s100, s50
	s_addc_u32 s101, s51, 0
	s_add_u32 s100, s100, s70
	s_addc_u32 s101, s101, s71
	s_add_u32 s100, s100, 0x1000
	s_addc_u32 s101, s101, 0
	v_or_b32_e32 v0, s84, v124
	v_mad_u64_u32 v[8:9], s[74:75], v0, s92, v[140:141]
	ds_read_b128 v[0:3], v8
	ds_read_b128 v[4:7], v8 offset:32
	v_or_b32_e32 v126, s84, v145
	v_lshl_add_u64 v[166:167], s[66:67], 0, v[126:127]
	s_waitcnt lgkmcnt(1)
	v_mfma_f32_32x32x16_bf16 v[64:79], v[0:3], v[48:51], 0
	s_waitcnt lgkmcnt(0)
	v_mfma_f32_32x32x16_bf16 v[64:79], v[4:7], v[108:111], v[64:79]
	ds_read_b128 v[0:3], v8 offset:64
	ds_read_b128 v[4:7], v8 offset:96
	s_waitcnt lgkmcnt(1)
	v_mfma_f32_32x32x16_bf16 v[64:79], v[0:3], v[104:107], v[64:79]
	s_waitcnt lgkmcnt(0)
	v_mfma_f32_32x32x16_bf16 v[64:79], v[4:7], v[120:123], v[64:79]
	ds_read_b128 v[0:3], v153
	ds_read_b128 v[4:7], v153 offset:32
	s_waitcnt lgkmcnt(1)
	v_mfma_f32_32x32x16_bf16 v[32:47], v[0:3], v[48:51], 0
	s_waitcnt lgkmcnt(0)
	v_mfma_f32_32x32x16_bf16 v[32:47], v[4:7], v[108:111], v[32:47]
	ds_read_b128 v[0:3], v153 offset:64
	ds_read_b128 v[4:7], v153 offset:96
	s_waitcnt lgkmcnt(1)
	v_mfma_f32_32x32x16_bf16 v[32:47], v[0:3], v[104:107], v[32:47]
	s_waitcnt lgkmcnt(0)
	v_mfma_f32_32x32x16_bf16 v[32:47], v[4:7], v[120:123], v[32:47]
	ds_read_b128 v[0:3], v153 offset:4608
	ds_read_b128 v[4:7], v153 offset:4640
	ds_read_b128 v[52:55], v153 offset:9248
	s_waitcnt lgkmcnt(2)
	v_mfma_f32_32x32x16_bf16 v[16:31], v[0:3], v[48:51], 0
	ds_read_b128 v[0:3], v153 offset:4672
	s_waitcnt lgkmcnt(2)
	v_mfma_f32_32x32x16_bf16 v[16:31], v[4:7], v[108:111], v[16:31]
	ds_read_b128 v[4:7], v153 offset:4704
	s_waitcnt lgkmcnt(1)
	v_mfma_f32_32x32x16_bf16 v[16:31], v[0:3], v[104:107], v[16:31]
	ds_read_b128 v[0:3], v153 offset:9216
	s_waitcnt lgkmcnt(1)
	v_mfma_f32_32x32x16_bf16 v[16:31], v[4:7], v[120:123], v[16:31]
	s_waitcnt lgkmcnt(0)
	v_mfma_f32_32x32x16_bf16 v[0:15], v[0:3], v[48:51], 0
	ds_read_b128 v[56:59], v153 offset:9280
	v_mfma_f32_32x32x16_bf16 v[0:15], v[52:55], v[108:111], v[0:15]
	global_load_dwordx4 v[116:119], v231, s[100:101] nt
	global_load_dwordx4 v[112:115], v232, s[100:101] nt
	ds_read_b128 v[52:55], v153 offset:9312
	ds_read_b128 v[198:201], v153 offset:13856
	s_waitcnt lgkmcnt(2)
	v_mfma_f32_32x32x16_bf16 v[0:15], v[56:59], v[104:107], v[0:15]
	ds_read_b128 v[56:59], v153 offset:13824
	s_waitcnt lgkmcnt(2)
	v_mfma_f32_32x32x16_bf16 v[0:15], v[52:55], v[120:123], v[0:15]
	ds_read_b128 v[202:205], v153 offset:13888
	s_waitcnt lgkmcnt(1)
	v_mfma_f32_32x32x16_bf16 v[48:63], v[56:59], v[48:51], 0
	v_mfma_f32_32x32x16_bf16 v[48:63], v[198:201], v[108:111], v[48:63]
	ds_read_b128 v[198:201], v153 offset:13920
	s_andn2_b64 vcc, exec, s[72:73]
	s_waitcnt lgkmcnt(1)
	v_mfma_f32_32x32x16_bf16 v[48:63], v[202:205], v[104:107], v[48:63]
	global_load_dwordx4 v[108:111], v233, s[100:101] nt
	global_load_dwordx4 v[104:107], v234, s[100:101] nt
	s_waitcnt lgkmcnt(0)
	v_mfma_f32_32x32x16_bf16 v[48:63], v[198:201], v[120:123], v[48:63]
	s_cbranch_vccz .LBB0_319
	v_cndmask_b32_e64 v120, v188, v64, s[8:9]
	v_cndmask_b32_e64 v189, v65, v188, s[10:11]
	v_cndmask_b32_e64 v161, v188, v66, s[12:13]
	v_cndmask_b32_e64 v159, v188, v67, s[14:15]
	v_cndmask_b32_e64 v157, v188, v68, s[16:17]
	v_cndmask_b32_e64 v126, v188, v69, s[18:19]
	v_cndmask_b32_e64 v123, v188, v70, s[20:21]
	v_cndmask_b32_e64 v122, v188, v71, s[22:23]
	v_cndmask_b32_e64 v121, v188, v72, s[24:25]
	v_cndmask_b32_e64 v73, v188, v73, s[26:27]
	v_cndmask_b32_e64 v72, v188, v74, s[28:29]
	v_cndmask_b32_e64 v71, v188, v75, s[30:31]
	v_cndmask_b32_e64 v70, v188, v76, s[34:35]
	v_cndmask_b32_e64 v69, v188, v77, s[36:37]
	v_cndmask_b32_e64 v68, v188, v78, s[38:39]
	v_cndmask_b32_e64 v67, v188, v79, s[40:41]
	s_branch .LBB0_320

.LBB0_522:
	s_nop 0
	s_nop 0
	s_nop 0
	s_nop 0
	s_nop 0
	s_nop 0
	s_nop 0
	s_nop 0
	s_nop 0
	s_nop 0
	s_nop 0
	s_nop 0
	s_nop 0
	s_nop 0
	s_cmp_lt_i32 s80, 7
	s_cselect_b64 s[0:1], -1, 0
	s_cmp_gt_i32 s81, 6
	s_cselect_b64 s[4:5], -1, 0
	s_and_b64 s[0:1], s[0:1], s[4:5]
	s_andn2_b64 vcc, exec, s[0:1]
	s_cbranch_vccnz .LBB0_622
	v_lshrrev_b32_e32 v2, 1, v144
	v_lshrrev_b32_e32 v3, 5, v144
	v_and_b32_e32 v2, 24, v2
	v_and_b32_e32 v3, 4, v3
	v_bfe_u32 v4, v144, 2, 2
	v_lshlrev_b32_e32 v0, 4, v144
	v_and_b32_e32 v1, 32, v144
	v_bfe_u32 v10, v144, 2, 4
	v_or3_b32 v2, v3, v4, v2
	v_lshrrev_b32_e32 v3, 3, v144
	s_movk_i32 s0, 0x70
	v_bitop3_b32 v8, v0, v1, 48 bitop3:0x6c
	v_and_b32_e32 v9, 64, v144
	v_and_or_b32 v4, v3, s0, v10
	s_movk_i32 s0, 0x60
	v_add_u32_e32 v11, 0x2000, v0
	v_or_b32_e32 v1, v8, v9
	v_and_or_b32 v3, v3, s0, v2
	v_lshrrev_b32_e32 v0, 7, v11
	s_movk_i32 s0, 0xf0
	s_add_u32 s30, s62, 0x4000000
	v_lshl_or_b32 v150, v4, 12, v1
	v_and_or_b32 v3, v0, s0, v10
	s_movk_i32 s0, 0xe0
	s_addc_u32 s31, s63, 0
	v_and_or_b32 v0, v0, s0, v2
	s_lshl_b32 s0, s2, 2
	s_and_b32 s0, s0, 28
	s_ashr_i32 s1, s2, 6
	s_add_i32 s0, s0, s1
	s_waitcnt lgkmcnt(0)
	s_bfe_u32 s16, s2, 0x30003
	s_ashr_i32 s1, s0, 31
	s_lshl_b64 s[6:7], s[0:1], 20
	s_lshl_b32 s2, s16, 20
	s_add_u32 s1, s62, s2
	s_addc_u32 s3, s63, 0
	s_add_u32 s4, s1, 0x1200000
	s_addc_u32 s5, s3, 0
	s_add_u32 s8, s1, 0x1280000
	s_addc_u32 s9, s3, 0
	s_add_u32 s6, s30, s6
	s_addc_u32 s7, s31, s7
	s_add_u32 s10, s6, 0x80000
	v_readfirstlane_b32 s3, v144
	s_addc_u32 s11, s7, 0
	s_lshr_b32 s18, s3, 6
	s_lshl_b32 s1, s18, 10
	s_add_i32 s34, s1, 0
	s_add_i32 m0, s34, 0x10000
	v_lshl_or_b32 v154, v3, 12, v1
	global_load_lds_dwordx4 v150, s[4:5]
	s_add_i32 m0, s34, 0x12000
	v_lshl_or_b32 v148, v4, 12, v1
	global_load_lds_dwordx4 v154, s[4:5]
	s_add_i32 m0, s34, 0x14000
	s_add_i32 s35, s34, 0x2000
	global_load_lds_dwordx4 v150, s[8:9]
	s_add_i32 m0, s34, 0x16000
	v_lshl_or_b32 v152, v3, 12, v1
	global_load_lds_dwordx4 v154, s[8:9]
	s_mov_b32 m0, s34
	s_add_i32 s36, s34, 0x4000
	global_load_lds_dwordx4 v148, s[6:7]
	s_mov_b32 m0, s35
	s_add_i32 s37, s34, 0x6000
	global_load_lds_dwordx4 v152, s[6:7]
	s_mov_b32 m0, s36
	v_mov_b32_e32 v151, 0
	global_load_lds_dwordx4 v148, s[10:11]
	s_mov_b32 m0, s37
	s_lshr_b32 s19, s3, 8
	global_load_lds_dwordx4 v152, s[10:11]
	v_mov_b32_e32 v155, v151
	v_mov_b32_e32 v149, v151
	v_mov_b32_e32 v153, v151
	s_cmp_eq_u32 s19, 1
	s_mov_b32 s38, 0
	v_lshl_add_u64 v[0:1], s[4:5], 0, v[150:151]
	v_lshl_add_u64 v[2:3], s[4:5], 0, v[154:155]
	v_lshl_add_u64 v[4:5], s[6:7], 0, v[148:149]
	s_cselect_b64 s[8:9], -1, 0
	s_cmp_lg_u32 s19, 1
	v_lshl_add_u64 v[6:7], s[6:7], 0, v[152:153]
	s_cbranch_scc1 .LBB0_525
	s_barrier
